# grid barrier: non-leader workgroups acquire with an L1-only invalidate (their XCD leader already invalidated the shared L2 before releasing them)
# speedup vs baseline: 1.0106x; 1.0106x over previous
; __device__ __forceinline__ unsigned xb_ld(unsigned* p)              { return __hip_atomic_load(p, __ATOMIC_RELAXED, __HIP_MEMORY_SCOPE_AGENT); }
; #define XB_SPIN(cond, bar) do { unsigned _sp = 0; while (cond) { __builtin_amdgcn_s_sleep(1); \
;     if ((++_sp & 255u) == 0u) { if (xb_ld(&(bar)[XB_TMO])) break; if (_sp > XB_SPIN_CAP) { atomicAdd(&(bar)[XB_TMO], 1u); break; } } } } while (0)
; __device__ __forceinline__ void xcd_barrier(const XcdBarrier& b) {
;     ...
;         } else {
;             XB_SPIN(xb_ld(&bar[XB_XGEN(b.x)]) == gen, bar);
;             __builtin_amdgcn_fence(__ATOMIC_ACQUIRE, "agent");
;             asm volatile("s_waitcnt vmcnt(0)" ::: "memory");
.LBB0_114:
	s_or_b64 exec, exec, s[12:13]
	s_waitcnt vmcnt(0)
	buffer_inv sc0
	s_waitcnt vmcnt(0)

; __device__ __forceinline__ unsigned xb_ld(unsigned* p)              { return __hip_atomic_load(p, __ATOMIC_RELAXED, __HIP_MEMORY_SCOPE_AGENT); }
; #define XB_SPIN(cond, bar) do { unsigned _sp = 0; while (cond) { __builtin_amdgcn_s_sleep(1); \
;     if ((++_sp & 255u) == 0u) { if (xb_ld(&(bar)[XB_TMO])) break; if (_sp > XB_SPIN_CAP) { atomicAdd(&(bar)[XB_TMO], 1u); break; } } } } while (0)
; __device__ __forceinline__ void xcd_barrier(const XcdBarrier& b) {
;     ...
;         } else {
;             XB_SPIN(xb_ld(&bar[XB_XGEN(b.x)]) == gen, bar);
;             __builtin_amdgcn_fence(__ATOMIC_ACQUIRE, "agent");
;             asm volatile("s_waitcnt vmcnt(0)" ::: "memory");
.LBB0_470:
	s_or_b64 exec, exec, s[10:11]
	s_waitcnt vmcnt(0)
	buffer_inv sc0
	s_waitcnt vmcnt(0)

; __device__ __forceinline__ unsigned xb_ld(unsigned* p)              { return __hip_atomic_load(p, __ATOMIC_RELAXED, __HIP_MEMORY_SCOPE_AGENT); }
; #define XB_SPIN(cond, bar) do { unsigned _sp = 0; while (cond) { __builtin_amdgcn_s_sleep(1); \
;     if ((++_sp & 255u) == 0u) { if (xb_ld(&(bar)[XB_TMO])) break; if (_sp > XB_SPIN_CAP) { atomicAdd(&(bar)[XB_TMO], 1u); break; } } } } while (0)
; __device__ __forceinline__ void xcd_barrier(const XcdBarrier& b) {
;     ...
;         } else {
;             XB_SPIN(xb_ld(&bar[XB_XGEN(b.x)]) == gen, bar);
;             __builtin_amdgcn_fence(__ATOMIC_ACQUIRE, "agent");
;             asm volatile("s_waitcnt vmcnt(0)" ::: "memory");
.LBB0_981:
	s_or_b64 exec, exec, s[8:9]
	s_waitcnt vmcnt(0)
	buffer_inv sc0
	s_waitcnt vmcnt(0)
